# phase 0 modulation GEMV: the 16 loads of the next iteration are issued while the current ones are consumed
# baseline (speedup 1.0000x reference)
; DI void phase0(const Params& P, char* smem) {
;     ...
;       int mi = t - NT - NF, l = mi / 96, col0 = (mi % 96) * 64;
;       float* scond = tile; float* red = tile + 9216;
;       for (int idx = tid; idx < 9216; idx += 256) {
;         int n = idx >> 10, k = idx & 1023; float v = n < 8 ? P.c[n * 1024 + k] : P.c_ctx[k];
;         scond[idx] = v / (1.f + expf(-v));
;       }
;       __syncthreads();
;       int col = tid & 63, kq = tid >> 6; float acc[9];
; #pragma unroll
;       for (int n = 0; n < 9; n++) acc[n] = 0.f;
;       const float* w = P.w_mod + ((size_t)l * 1024 + kq * 256) * 6144 + col0 + col;
; #pragma unroll 16
;       for (int k = 0; k < 256; k++) {
;         float wv = w[(size_t)k * 6144];
; #pragma unroll
;         for (int n = 0; n < 9; n++) acc[n] += scond[n * 1024 + kq * 256 + k] * wv;
.LBB0_107:
	s_or_b64 exec, exec, s[48:49]
	s_add_i32 s28, s85, 0xffffe600
	s_cmpk_gt_u32 s28, 0x5f
	s_cselect_b64 s[0:1], -1, 0
	s_add_i32 s29, s85, 0xffffe5a0
	s_cmpk_lt_u32 s28, 0x60
	s_cselect_b32 s28, s28, s29
	s_lshl_b32 s78, s28, 6
	s_and_b64 s[28:29], s[0:1], exec
	s_cselect_b32 s28, 0x400, 0
	s_mov_b32 s29, s79
	v_lshl_add_u64 v[6:7], s[28:29], 0, v[18:19]
	v_mov_b64_e32 v[8:9], s[64:65]
	v_mad_u64_u32 v[8:9], s[28:29], v6, s23, v[8:9]
	v_mad_i32_i24 v9, v7, s23, v9
	v_lshl_add_u64 v[6:7], s[78:79], 2, v[8:9]
	v_lshlrev_b32_e32 v20, 2, v16
	v_mov_b32_e32 v96, 0
	v_lshl_add_u64 v[6:7], v[6:7], 0, v[20:21]
	s_mov_b64 s[48:49], 0
	v_mov_b32_e32 v69, v11
	v_mov_b32_e32 v97, v96
	v_mov_b32_e32 v98, v96
	v_mov_b32_e32 v99, v96
	v_mov_b32_e32 v94, v96
	v_mov_b32_e32 v95, v96
	v_mov_b32_e32 v92, v96
	v_mov_b32_e32 v93, v96
	v_mov_b32_e32 v71, v96
	s_waitcnt lgkmcnt(0)
	s_mov_b64 s[100:101], 0x6000
	v_mov_b32_e32 v186, v6
	v_mov_b32_e32 v187, v7
	global_load_dword v188, v[6:7], off
	v_lshl_add_u64 v[186:187], v[186:187], 0, s[100:101]
	global_load_dword v189, v[186:187], off
	v_lshl_add_u64 v[186:187], v[186:187], 0, s[100:101]
	global_load_dword v190, v[186:187], off
	v_lshl_add_u64 v[186:187], v[186:187], 0, s[100:101]
	global_load_dword v191, v[186:187], off
	v_lshl_add_u64 v[186:187], v[186:187], 0, s[100:101]
	global_load_dword v192, v[186:187], off
	v_lshl_add_u64 v[186:187], v[186:187], 0, s[100:101]
	global_load_dword v193, v[186:187], off
	v_lshl_add_u64 v[186:187], v[186:187], 0, s[100:101]
	global_load_dword v194, v[186:187], off
	v_lshl_add_u64 v[186:187], v[186:187], 0, s[100:101]
	global_load_dword v195, v[186:187], off
	v_lshl_add_u64 v[186:187], v[186:187], 0, s[100:101]
	global_load_dword v196, v[186:187], off
	v_lshl_add_u64 v[186:187], v[186:187], 0, s[100:101]
	global_load_dword v197, v[186:187], off
	v_lshl_add_u64 v[186:187], v[186:187], 0, s[100:101]
	global_load_dword v198, v[186:187], off
	v_lshl_add_u64 v[186:187], v[186:187], 0, s[100:101]
	global_load_dword v199, v[186:187], off
	v_lshl_add_u64 v[186:187], v[186:187], 0, s[100:101]
	global_load_dword v200, v[186:187], off
	v_lshl_add_u64 v[186:187], v[186:187], 0, s[100:101]
	global_load_dword v201, v[186:187], off
	v_lshl_add_u64 v[186:187], v[186:187], 0, s[100:101]
	global_load_dword v202, v[186:187], off
	v_lshl_add_u64 v[186:187], v[186:187], 0, s[100:101]
	global_load_dword v203, v[186:187], off
	s_barrier
.LBB0_108:
	v_lshl_add_u64 v[8:9], v[6:7], 0, s[48:49]
	ds_read_b128 v[154:157], v69
	ds_read_b128 v[158:161], v69 offset:16
	ds_read_b128 v[126:129], v69 offset:32
	ds_read_b128 v[122:125], v69 offset:48
	ds_read_b128 v[132:135], v69 offset:4096
	s_waitcnt lgkmcnt(4)
	v_mov_b32_e32 v136, v154
	v_add_co_u32_e32 v152, vcc, s23, v8
	s_mov_b32 s28, 0xc000
	s_waitcnt lgkmcnt(0)
	v_mov_b32_e32 v137, v132
	v_addc_co_u32_e32 v153, vcc, 0, v9, vcc
	v_mov_b32_e32 v132, v155
	s_add_u32 s48, s48, 0x60000
	s_addc_u32 s49, s49, 0
	s_cmp_eq_u32 s48, 0x600000
	s_cselect_b32 s98, 0x5a0000, s48
	s_mov_b32 s99, 0
	v_lshl_add_u64 v[186:187], v[6:7], 0, s[98:99]
	s_waitcnt vmcnt(15)
	v_mov_b32_e32 v20, v188
	global_load_dword v188, v[186:187], off
	v_lshl_add_u64 v[186:187], v[186:187], 0, s[100:101]
	v_pk_fma_f32 v[144:145], v[20:21], v[136:137], v[96:97] op_sel_hi:[0,1,1]
	ds_read_b128 v[162:165], v69 offset:8192
	ds_read_b128 v[136:139], v69 offset:12288
	s_waitcnt lgkmcnt(1)
	v_mov_b32_e32 v96, v162
	s_waitcnt lgkmcnt(0)
	v_mov_b32_e32 v97, v136
	v_pk_fma_f32 v[146:147], v[20:21], v[96:97], v[98:99] op_sel_hi:[0,1,1]
	ds_read_b128 v[166:169], v69 offset:16384
	ds_read_b128 v[96:99], v69 offset:20480
	v_mov_b32_e32 v136, v163
	s_waitcnt lgkmcnt(1)
	v_mov_b32_e32 v140, v166
	s_waitcnt lgkmcnt(0)
	v_mov_b32_e32 v141, v96
	v_pk_fma_f32 v[148:149], v[20:21], v[140:141], v[94:95] op_sel_hi:[0,1,1]
	ds_read_b128 v[174:177], v69 offset:24576
	ds_read_b128 v[140:143], v69 offset:28672
	v_mov_b32_e32 v96, v167
	s_waitcnt lgkmcnt(1)
	v_mov_b32_e32 v94, v174
	s_waitcnt lgkmcnt(0)
	v_mov_b32_e32 v95, v140
	v_pk_fma_f32 v[150:151], v[20:21], v[94:95], v[92:93] op_sel_hi:[0,1,1]
	ds_read_b128 v[92:95], v69 offset:32768
	v_mov_b32_e32 v140, v175
	s_waitcnt lgkmcnt(0)
	v_fmac_f32_e32 v71, v20, v92
	v_add_co_u32_e32 v92, vcc, s28, v8
	s_mov_b32 s28, 0x12000
	s_waitcnt vmcnt(15)
	v_mov_b32_e32 v20, v189
	global_load_dword v189, v[186:187], off
	v_lshl_add_u64 v[186:187], v[186:187], 0, s[100:101]
	v_fmac_f32_e32 v71, v20, v93
	v_addc_co_u32_e32 v93, vcc, 0, v9, vcc
	v_pk_fma_f32 v[132:133], v[20:21], v[132:133], v[144:145] op_sel_hi:[0,1,1]
	v_pk_fma_f32 v[136:137], v[20:21], v[136:137], v[146:147] op_sel_hi:[0,1,1]
	v_pk_fma_f32 v[96:97], v[20:21], v[96:97], v[148:149] op_sel_hi:[0,1,1]
	v_pk_fma_f32 v[140:141], v[20:21], v[140:141], v[150:151] op_sel_hi:[0,1,1]
	v_mov_b32_e32 v92, v156
	v_mov_b32_e32 v93, v134
	v_mov_b32_e32 v134, v157
	s_waitcnt vmcnt(15)
	v_mov_b32_e32 v20, v190
	global_load_dword v190, v[186:187], off
	v_lshl_add_u64 v[186:187], v[186:187], 0, s[100:101]
	v_pk_fma_f32 v[92:93], v[20:21], v[92:93], v[132:133] op_sel_hi:[0,1,1]
	v_mov_b32_e32 v132, v164
	v_mov_b32_e32 v133, v138
	v_pk_fma_f32 v[132:133], v[20:21], v[132:133], v[136:137] op_sel_hi:[0,1,1]
	v_mov_b32_e32 v136, v168
	v_mov_b32_e32 v137, v98
	v_pk_fma_f32 v[96:97], v[20:21], v[136:137], v[96:97] op_sel_hi:[0,1,1]
	v_mov_b32_e32 v136, v176
	v_mov_b32_e32 v137, v142
	v_pk_fma_f32 v[136:137], v[20:21], v[136:137], v[140:141] op_sel_hi:[0,1,1]
	v_add_co_u32_e32 v140, vcc, s28, v8
	v_fmac_f32_e32 v71, v20, v94
	s_nop 0
	v_addc_co_u32_e32 v141, vcc, 0, v9, vcc
	v_mov_b32_e32 v138, v165
	v_mov_b32_e32 v98, v169
	v_mov_b32_e32 v142, v177
	s_mov_b32 s28, 0x1e000
	s_waitcnt vmcnt(15)
; DI void phase0(const Params& P, char* smem) {
;     ...
;       for (int k = 0; k < 256; k++) {
;         float wv = w[(size_t)k * 6144];
; #pragma unroll
;         for (int n = 0; n < 9; n++) acc[n] += scond[n * 1024 + kq * 256 + k] * wv;
	v_mov_b32_e32 v20, v191
	global_load_dword v191, v[186:187], off
	v_lshl_add_u64 v[186:187], v[186:187], 0, s[100:101]
	v_pk_fma_f32 v[134:135], v[20:21], v[134:135], v[92:93] op_sel_hi:[0,1,1]
	v_add_co_u32_e32 v92, vcc, s27, v8
	v_pk_fma_f32 v[132:133], v[20:21], v[138:139], v[132:133] op_sel_hi:[0,1,1]
	s_nop 0
	v_addc_co_u32_e32 v93, vcc, 0, v9, vcc
	v_pk_fma_f32 v[138:139], v[20:21], v[98:99], v[96:97] op_sel_hi:[0,1,1]
	v_pk_fma_f32 v[140:141], v[20:21], v[142:143], v[136:137] op_sel_hi:[0,1,1]
	v_fmac_f32_e32 v71, v20, v95
	ds_read_b128 v[92:95], v69 offset:4112
	v_mov_b32_e32 v96, v158
	v_add_co_u32_e32 v152, vcc, s28, v8
	s_mov_b32 s28, 0x24000
	s_waitcnt lgkmcnt(0)
	v_mov_b32_e32 v97, v92
	v_addc_co_u32_e32 v153, vcc, 0, v9, vcc
	v_mov_b32_e32 v92, v159
	s_waitcnt vmcnt(15)
	v_mov_b32_e32 v20, v192
	global_load_dword v192, v[186:187], off
	v_lshl_add_u64 v[186:187], v[186:187], 0, s[100:101]
	v_pk_fma_f32 v[144:145], v[20:21], v[96:97], v[134:135] op_sel_hi:[0,1,1]
	ds_read_b128 v[154:157], v69 offset:8208
	ds_read_b128 v[96:99], v69 offset:12304
	s_waitcnt lgkmcnt(1)
	v_mov_b32_e32 v134, v154
	s_waitcnt lgkmcnt(0)
	v_mov_b32_e32 v135, v96
	v_pk_fma_f32 v[146:147], v[20:21], v[134:135], v[132:133] op_sel_hi:[0,1,1]
	ds_read_b128 v[162:165], v69 offset:16400
	ds_read_b128 v[132:135], v69 offset:20496
	v_mov_b32_e32 v96, v155
	s_waitcnt lgkmcnt(1)
	v_mov_b32_e32 v136, v162
	s_waitcnt lgkmcnt(0)
	v_mov_b32_e32 v137, v132
	v_pk_fma_f32 v[148:149], v[20:21], v[136:137], v[138:139] op_sel_hi:[0,1,1]
	ds_read_b128 v[166:169], v69 offset:24592
	ds_read_b128 v[136:139], v69 offset:28688
	v_mov_b32_e32 v132, v163
	s_waitcnt lgkmcnt(1)
	v_mov_b32_e32 v142, v166
	s_waitcnt lgkmcnt(0)
	v_mov_b32_e32 v143, v136
	v_pk_fma_f32 v[150:151], v[20:21], v[142:143], v[140:141] op_sel_hi:[0,1,1]
	ds_read_b128 v[140:143], v69 offset:32784
	v_mov_b32_e32 v136, v167
	s_waitcnt lgkmcnt(0)
	v_fmac_f32_e32 v71, v20, v140
	v_add_co_u32_e32 v140, vcc, s28, v8
	s_mov_b32 s28, 0x2a000
	s_waitcnt vmcnt(15)
	v_mov_b32_e32 v20, v193
	global_load_dword v193, v[186:187], off
	v_lshl_add_u64 v[186:187], v[186:187], 0, s[100:101]
	v_fmac_f32_e32 v71, v20, v141
	v_addc_co_u32_e32 v141, vcc, 0, v9, vcc
	v_pk_fma_f32 v[92:93], v[20:21], v[92:93], v[144:145] op_sel_hi:[0,1,1]
	v_pk_fma_f32 v[96:97], v[20:21], v[96:97], v[146:147] op_sel_hi:[0,1,1]
	v_pk_fma_f32 v[132:133], v[20:21], v[132:133], v[148:149] op_sel_hi:[0,1,1]
	v_pk_fma_f32 v[136:137], v[20:21], v[136:137], v[150:151] op_sel_hi:[0,1,1]
	v_mov_b32_e32 v140, v160
	v_mov_b32_e32 v141, v94
	v_mov_b32_e32 v94, v161
	s_waitcnt vmcnt(15)
	v_mov_b32_e32 v20, v194
	global_load_dword v194, v[186:187], off
	v_lshl_add_u64 v[186:187], v[186:187], 0, s[100:101]
	v_pk_fma_f32 v[92:93], v[20:21], v[140:141], v[92:93] op_sel_hi:[0,1,1]
	v_mov_b32_e32 v140, v156
	v_mov_b32_e32 v141, v98
	v_pk_fma_f32 v[96:97], v[20:21], v[140:141], v[96:97] op_sel_hi:[0,1,1]
	v_mov_b32_e32 v140, v164
	v_mov_b32_e32 v141, v134
	v_pk_fma_f32 v[132:133], v[20:21], v[140:141], v[132:133] op_sel_hi:[0,1,1]
	v_mov_b32_e32 v140, v168
	v_mov_b32_e32 v141, v138
	v_pk_fma_f32 v[136:137], v[20:21], v[140:141], v[136:137] op_sel_hi:[0,1,1]
	v_add_co_u32_e32 v140, vcc, s28, v8
	v_fmac_f32_e32 v71, v20, v142
	s_nop 0
	v_addc_co_u32_e32 v141, vcc, 0, v9, vcc
	s_mov_b32 s28, 0x30000
	v_mov_b32_e32 v98, v157
	v_mov_b32_e32 v134, v165
	v_mov_b32_e32 v138, v169
	s_waitcnt vmcnt(15)
	v_mov_b32_e32 v20, v195
	global_load_dword v195, v[186:187], off
	v_lshl_add_u64 v[186:187], v[186:187], 0, s[100:101]
	v_pk_fma_f32 v[140:141], v[20:21], v[94:95], v[92:93] op_sel_hi:[0,1,1]
	v_add_co_u32_e32 v92, vcc, s28, v8
	v_pk_fma_f32 v[144:145], v[20:21], v[98:99], v[96:97] op_sel_hi:[0,1,1]
	s_nop 0
	v_addc_co_u32_e32 v93, vcc, 0, v9, vcc
	v_pk_fma_f32 v[146:147], v[20:21], v[134:135], v[132:133] op_sel_hi:[0,1,1]
	v_pk_fma_f32 v[148:149], v[20:21], v[138:139], v[136:137] op_sel_hi:[0,1,1]
	v_fmac_f32_e32 v71, v20, v143
	ds_read_b128 v[92:95], v69 offset:4128
	v_mov_b32_e32 v96, v126
	s_mov_b32 s28, 0x36000
	v_add_co_u32_e32 v152, vcc, s28, v8
	s_waitcnt lgkmcnt(0)
	v_mov_b32_e32 v97, v92
	v_addc_co_u32_e32 v153, vcc, 0, v9, vcc
	s_mov_b32 s28, 0x3c000
	v_mov_b32_e32 v92, v127
	s_waitcnt vmcnt(15)
	v_mov_b32_e32 v20, v196
	global_load_dword v196, v[186:187], off
	v_lshl_add_u64 v[186:187], v[186:187], 0, s[100:101]
	v_pk_fma_f32 v[150:151], v[20:21], v[96:97], v[140:141] op_sel_hi:[0,1,1]
	ds_read_b128 v[154:157], v69 offset:8224
	ds_read_b128 v[96:99], v69 offset:12320
	s_waitcnt lgkmcnt(1)
	v_mov_b32_e32 v132, v154
	s_waitcnt lgkmcnt(0)
	v_mov_b32_e32 v133, v96
	v_pk_fma_f32 v[144:145], v[20:21], v[132:133], v[144:145] op_sel_hi:[0,1,1]
	ds_read_b128 v[158:161], v69 offset:16416
	ds_read_b128 v[132:135], v69 offset:20512
	v_mov_b32_e32 v96, v155
	s_waitcnt lgkmcnt(1)
	v_mov_b32_e32 v136, v158
	s_waitcnt lgkmcnt(0)
	v_mov_b32_e32 v137, v132
	v_pk_fma_f32 v[146:147], v[20:21], v[136:137], v[146:147] op_sel_hi:[0,1,1]
	ds_read_b128 v[162:165], v69 offset:24608
	ds_read_b128 v[136:139], v69 offset:28704
	v_mov_b32_e32 v132, v159
	s_waitcnt lgkmcnt(1)
	v_mov_b32_e32 v140, v162
	s_waitcnt lgkmcnt(0)
	v_mov_b32_e32 v141, v136
	v_pk_fma_f32 v[148:149], v[20:21], v[140:141], v[148:149] op_sel_hi:[0,1,1]
	ds_read_b128 v[140:143], v69 offset:32800
	v_mov_b32_e32 v136, v163
	s_waitcnt lgkmcnt(0)
	v_fmac_f32_e32 v71, v20, v140
	s_waitcnt vmcnt(15)
; DI void phase0(const Params& P, char* smem) {
;     ...
;       for (int k = 0; k < 256; k++) {
;         float wv = w[(size_t)k * 6144];
; #pragma unroll
;         for (int n = 0; n < 9; n++) acc[n] += scond[n * 1024 + kq * 256 + k] * wv;
;       }
; #pragma unroll
;       for (int n = 0; n < 9; n++) red[(kq * 9 + n) * 64 + col] = acc[n];
;       __syncthreads();
;       for (int idx = tid; idx < 576; idx += 256) {
;         int n = idx / 64, cc = idx % 64;
;         float s = red[(0 * 9 + n) * 64 + cc] + red[(1 * 9 + n) * 64 + cc] + red[(2 * 9 + n) * 64 + cc] + red[(3 * 9 + n) * 64 + cc];
;         P.mod[(size_t)(l * 9 + n) * 6144 + col0 + cc] = s + P.b_mod[l * 6144 + col0 + cc];
	v_mov_b32_e32 v20, v197
	global_load_dword v197, v[186:187], off
	v_lshl_add_u64 v[186:187], v[186:187], 0, s[100:101]
	v_pk_fma_f32 v[126:127], v[20:21], v[132:133], v[146:147] op_sel_hi:[0,1,1]
	v_pk_fma_f32 v[132:133], v[20:21], v[136:137], v[148:149] op_sel_hi:[0,1,1]
	v_add_co_u32_e32 v136, vcc, s28, v8
	v_pk_fma_f32 v[92:93], v[20:21], v[92:93], v[150:151] op_sel_hi:[0,1,1]
	s_nop 0
	v_addc_co_u32_e32 v137, vcc, 0, v9, vcc
	v_pk_fma_f32 v[96:97], v[20:21], v[96:97], v[144:145] op_sel_hi:[0,1,1]
	v_fmac_f32_e32 v71, v20, v141
	v_mov_b32_e32 v136, v128
	v_mov_b32_e32 v137, v94
	s_mov_b32 s28, 0x42000
	v_mov_b32_e32 v94, v129
	s_waitcnt vmcnt(15)
	v_mov_b32_e32 v20, v198
	global_load_dword v198, v[186:187], off
	v_lshl_add_u64 v[186:187], v[186:187], 0, s[100:101]
	v_pk_fma_f32 v[92:93], v[20:21], v[136:137], v[92:93] op_sel_hi:[0,1,1]
	v_mov_b32_e32 v136, v156
	v_mov_b32_e32 v137, v98
	v_pk_fma_f32 v[96:97], v[20:21], v[136:137], v[96:97] op_sel_hi:[0,1,1]
	v_mov_b32_e32 v136, v160
	v_mov_b32_e32 v137, v134
	v_pk_fma_f32 v[126:127], v[20:21], v[136:137], v[126:127] op_sel_hi:[0,1,1]
	v_mov_b32_e32 v136, v164
	v_mov_b32_e32 v137, v138
	v_pk_fma_f32 v[132:133], v[20:21], v[136:137], v[132:133] op_sel_hi:[0,1,1]
	v_add_co_u32_e32 v136, vcc, s28, v8
	v_fmac_f32_e32 v71, v20, v142
	s_nop 0
	v_addc_co_u32_e32 v137, vcc, 0, v9, vcc
	s_mov_b32 s28, 0x48000
	v_mov_b32_e32 v98, v157
	v_mov_b32_e32 v134, v161
	v_mov_b32_e32 v138, v165
	s_waitcnt vmcnt(15)
	v_mov_b32_e32 v20, v199
	global_load_dword v199, v[186:187], off
	v_lshl_add_u64 v[186:187], v[186:187], 0, s[100:101]
	v_pk_fma_f32 v[128:129], v[20:21], v[94:95], v[92:93] op_sel_hi:[0,1,1]
	v_add_co_u32_e32 v92, vcc, s28, v8
	v_pk_fma_f32 v[136:137], v[20:21], v[98:99], v[96:97] op_sel_hi:[0,1,1]
	s_nop 0
	v_addc_co_u32_e32 v93, vcc, 0, v9, vcc
	v_pk_fma_f32 v[134:135], v[20:21], v[134:135], v[126:127] op_sel_hi:[0,1,1]
	v_pk_fma_f32 v[138:139], v[20:21], v[138:139], v[132:133] op_sel_hi:[0,1,1]
	v_fmac_f32_e32 v71, v20, v143
	ds_read_b128 v[92:95], v69 offset:4144
	v_mov_b32_e32 v96, v122
	s_mov_b32 s28, 0x4e000
	v_add_co_u32_e32 v148, vcc, s28, v8
	s_waitcnt lgkmcnt(0)
	v_mov_b32_e32 v97, v92
	v_addc_co_u32_e32 v149, vcc, 0, v9, vcc
	s_mov_b32 s28, 0x54000
	v_mov_b32_e32 v92, v123
	s_waitcnt vmcnt(15)
	v_mov_b32_e32 v20, v200
	global_load_dword v200, v[186:187], off
	v_lshl_add_u64 v[186:187], v[186:187], 0, s[100:101]
	v_pk_fma_f32 v[140:141], v[20:21], v[96:97], v[128:129] op_sel_hi:[0,1,1]
	ds_read_b128 v[150:153], v69 offset:8240
	ds_read_b128 v[96:99], v69 offset:12336
	s_waitcnt lgkmcnt(1)
	v_mov_b32_e32 v126, v150
	s_waitcnt lgkmcnt(0)
	v_mov_b32_e32 v127, v96
	v_pk_fma_f32 v[142:143], v[20:21], v[126:127], v[136:137] op_sel_hi:[0,1,1]
	ds_read_b128 v[154:157], v69 offset:16432
	ds_read_b128 v[126:129], v69 offset:20528
	v_mov_b32_e32 v96, v151
	s_waitcnt lgkmcnt(1)
	v_mov_b32_e32 v132, v154
	s_waitcnt lgkmcnt(0)
	v_mov_b32_e32 v133, v126
	v_pk_fma_f32 v[144:145], v[20:21], v[132:133], v[134:135] op_sel_hi:[0,1,1]
	ds_read_b128 v[158:161], v69 offset:24624
	ds_read_b128 v[132:135], v69 offset:28720
	v_mov_b32_e32 v126, v155
	s_waitcnt lgkmcnt(1)
	v_mov_b32_e32 v136, v158
	s_waitcnt lgkmcnt(0)
	v_mov_b32_e32 v137, v132
	v_pk_fma_f32 v[146:147], v[20:21], v[136:137], v[138:139] op_sel_hi:[0,1,1]
	ds_read_b128 v[136:139], v69 offset:32816
	v_mov_b32_e32 v132, v159
	v_add_u32_e32 v69, 64, v69
	s_waitcnt lgkmcnt(0)
	v_fmac_f32_e32 v71, v20, v136
	s_waitcnt vmcnt(15)
	v_mov_b32_e32 v20, v201
	global_load_dword v201, v[186:187], off
	v_lshl_add_u64 v[186:187], v[186:187], 0, s[100:101]
	v_pk_fma_f32 v[122:123], v[20:21], v[126:127], v[144:145] op_sel_hi:[0,1,1]
	v_pk_fma_f32 v[126:127], v[20:21], v[132:133], v[146:147] op_sel_hi:[0,1,1]
	v_add_co_u32_e32 v132, vcc, s28, v8
	v_pk_fma_f32 v[92:93], v[20:21], v[92:93], v[140:141] op_sel_hi:[0,1,1]
	s_nop 0
	v_addc_co_u32_e32 v133, vcc, 0, v9, vcc
	v_pk_fma_f32 v[96:97], v[20:21], v[96:97], v[142:143] op_sel_hi:[0,1,1]
	v_fmac_f32_e32 v71, v20, v137
	s_mov_b32 s28, 0x5a000
	v_add_co_u32_e32 v8, vcc, s28, v8
	s_nop 1
	v_addc_co_u32_e32 v9, vcc, 0, v9, vcc
	v_mov_b32_e32 v132, v124
	v_mov_b32_e32 v133, v94
	v_mov_b32_e32 v94, v125
	s_waitcnt vmcnt(15)
	v_mov_b32_e32 v20, v202
	global_load_dword v202, v[186:187], off
	v_lshl_add_u64 v[186:187], v[186:187], 0, s[100:101]
	v_pk_fma_f32 v[92:93], v[20:21], v[132:133], v[92:93] op_sel_hi:[0,1,1]
	v_mov_b32_e32 v132, v152
	v_mov_b32_e32 v133, v98
	v_pk_fma_f32 v[132:133], v[20:21], v[132:133], v[96:97] op_sel_hi:[0,1,1]
	v_mov_b32_e32 v96, v156
	v_mov_b32_e32 v97, v128
	v_pk_fma_f32 v[122:123], v[20:21], v[96:97], v[122:123] op_sel_hi:[0,1,1]
	v_mov_b32_e32 v96, v160
	v_mov_b32_e32 v97, v134
	v_pk_fma_f32 v[126:127], v[20:21], v[96:97], v[126:127] op_sel_hi:[0,1,1]
	v_fmac_f32_e32 v71, v20, v138
	v_mov_b32_e32 v98, v153
	v_mov_b32_e32 v128, v157
	v_mov_b32_e32 v134, v161
	s_waitcnt vmcnt(15)
	v_mov_b32_e32 v8, v203
	global_load_dword v203, v[186:187], off
	v_lshl_add_u64 v[186:187], v[186:187], 0, s[100:101]
	v_pk_fma_f32 v[96:97], v[8:9], v[94:95], v[92:93] op_sel_hi:[0,1,1]
	v_pk_fma_f32 v[98:99], v[8:9], v[98:99], v[132:133] op_sel_hi:[0,1,1]
	v_pk_fma_f32 v[94:95], v[8:9], v[128:129], v[122:123] op_sel_hi:[0,1,1]
	v_pk_fma_f32 v[92:93], v[8:9], v[134:135], v[126:127] op_sel_hi:[0,1,1]
	v_fmac_f32_e32 v71, v8, v139
	s_cbranch_scc0 .LBB0_108
	v_readlane_b32 s4, v255, 42
	v_readlane_b32 s5, v255, 43
	ds_write2st64_b32 v118, v96, v97 offset0:144 offset1:145
	ds_write2st64_b32 v118, v98, v99 offset0:146 offset1:147
	ds_write2st64_b32 v118, v94, v95 offset0:148 offset1:149
	ds_write2st64_b32 v118, v92, v93 offset0:150 offset1:151
	ds_write_b32 v118, v71 offset:38912
	s_waitcnt lgkmcnt(0)
	s_barrier
	s_and_saveexec_b64 s[46:47], s[4:5]
	s_cbranch_execz .LBB0_112
	s_and_b64 s[28:29], s[0:1], exec
	s_cselect_b32 s28, 0x1800, 0
	s_add_i32 s28, s78, s28
	s_and_b64 s[0:1], s[0:1], exec
	s_cselect_b32 s29, 9, 0
	s_lshl_b64 s[0:1], s[78:79], 2
	v_readlane_b32 s48, v253, 59
	v_readlane_b32 s49, v253, 60
	s_add_u32 s0, s48, s0
	s_addc_u32 s1, s49, s1
	s_mov_b64 s[48:49], 0
	v_mov_b32_e32 v6, v107
	v_mov_b32_e32 v7, v12
